# FF1 epilogue writes full 128B lines: weight-tile columns remapped so a wave's two 32-col groups are adjacent, DPP row_ror:8 regroup so each H store covers 8 rows x 128B
# speedup vs baseline: 1.0034x; 1.0034x over previous
;     __device__ __forceinline__ bool next(int i, Unit& u) const { return map(rank + i * nloc, u); }
; template <class Epi, class Sched, bool ALIGN_EPI = false, bool SP2 = false>
; __device__ __forceinline__ void gemm_phase(PG8_LAS unsigned char* lds, const Gemm g, const Sched& S, const Epi& E, int wid0) {
;     ...
;     unsigned voffA[2], voffB[2];
; #pragma unroll
;     for (int i = 0; i < 2; ++i) { int R, C; stage_rc(tid * 16 + i * 8192, R, C); const int Rb = Epi::PERM ? ((R & ~31) + perm32(R & 31)) : R;
;         voffA[i] = (unsigned)(R * LDA + C) * 2u; voffB[i] = (unsigned)(Rb * K + C) * 2u; }
;     const size_t kstep = (size_t)(BK * 2);
;     const size_t hstep = (size_t)HALF * K * 2;
;     const size_t tstep = 2 * hstep;
;     const size_t hstepA = (size_t)HALF * LDA * 2, tstepA = 2 * hstepA;
;     const unsigned ldsw = (unsigned)wid * 1024u;
;     const int aoff = lds_byte(wr * 64 + fr, fq * 8), boff = lds_byte(wc * 32 + fr, fq * 8);
;     ...
;     Unit cur, nxt; int ui = 0;
;     if (!S.next(0, cur)) return;
;     f32x4 acc[2][2][4][2];
; #pragma unroll
;     for (int a = 0; a < 2; ++a)
; #pragma unroll
;         for (int b = 0; b < 2; ++b)
; #pragma unroll
;             for (int m = 0; m < 4; ++m)
; #pragma unroll
;                 for (int n = 0; n < 2; ++n) acc[a][b][m][n] = (f32x4){0.f, 0.f, 0.f, 0.f};
;     bf16x8 At[4][2], B0[2][2], B1[2][2];
;     const char* cA = (const char*)g.A + (size_t)cur.pm * tstepA; const char* cB = (const char*)g.Bt + (size_t)cur.pn * tstep;
;     cur.ui = 0;
;     f32x4 pq0 = (f32x4){0.f, 0.f, 0.f, 0.f}, pq1 = pq0, pq2 = pq0;
;     if constexpr (Epi::HAS_PRE) E.pre_issue(cur, tid, pq0, pq1, pq2);
;     S.a_ready(cur);
;     if constexpr (SP2) {
;         PG8_STAGE(PG8_SB(0, 0), cB, voffB); PG8_STAGE(PG8_SB(0, 1), cB + hstep, voffB); PG8_STAGE(PG8_SA(0, 0), cA, voffA); PG8_STAGE(PG8_SA(0, 1), cA + hstepA, voffA);
;         if (wr == 1) PG8_BAR;
;         PG8_WAIT_V(2); PG8_BAR;
;         PG8_STAGE(PG8_SB(1, 0), cB + kstep, voffB); PG8_STAGE(PG8_SA(1, 0), cA + kstep, voffA); PG8_STAGE(PG8_SB(1, 1), cB + hstep + kstep, voffB);
;         PG8_WAIT_V(6); PG8_BAR;
;     } else {
;         PG8_STAGE(PG8_SB(0, 0), cB, voffB); PG8_STAGE(PG8_SA(0, 0), cA, voffA); PG8_STAGE(PG8_SB(0, 1), cB + hstep, voffB); PG8_STAGE(PG8_SA(0, 1), cA + hstepA, voffA);
;         if (wr == 1) PG8_BAR;
;         PG8_WAIT_V(4); PG8_BAR;
.LBB13_1062:
	s_or_b64 exec, exec, s[8:9]
	v_ashrrev_i32_e32 v8, 31, v169
	v_lshrrev_b32_e32 v8, 22, v8
	v_add_u32_e32 v8, v169, v8
	v_ashrrev_i32_e32 v8, 10, v8
	v_mul_i32_i24_e32 v15, 0x400, v8
	v_sub_u32_e32 v15, v169, v15
	s_lshl_b64 s[6:7], s[6:7], 15
	v_lshrrev_b32_e32 v16, 4, v15
	s_add_u32 s33, s18, 0x4000000
	v_bitop3_b32 v15, v16, v15, 32 bitop3:0x6c
	s_addc_u32 s42, s19, 0
	v_ashrrev_i32_e32 v17, 31, v15
	s_add_u32 s43, s18, 0x1680000
	v_lshrrev_b32_e32 v17, 26, v17
	s_addc_u32 s44, s19, 0
	s_ashr_i32 s27, s26, 31
	v_add_u32_e32 v17, v15, v17
	s_lshl_b64 s[8:9], s[26:27], 19
	v_ashrrev_i32_e32 v18, 6, v17
	v_and_b32_e32 v17, 0xc0, v17
	s_add_u32 s8, s33, s8
	v_sub_u32_e32 v15, v15, v17
	v_mov_b32_e32 v17, 1
	s_addc_u32 s9, s42, s9
	s_ashr_i32 s29, s28, 31
	v_lshlrev_b32_e32 v16, 3, v8
	v_lshlrev_b32_e32 v8, 5, v8
	v_ashrrev_i16_sdwa v15, v17, sext(v15) dst_sel:DWORD dst_unused:UNUSED_PAD src0_sel:DWORD src1_sel:BYTE_0
	s_lshl_b64 s[12:13], s[28:29], 19
	v_and_b32_e32 v16, -16, v16
	v_and_b32_e32 v8, 32, v8
	v_bfe_i32 v15, v15, 0, 16
	s_add_u32 s34, s43, s12
	v_add_u32_e32 v16, v18, v16
	v_and_b32_e32 v18, 3, v18
	s_mov_b32 s12, 0x1fffe0
	v_add_lshl_u32 v8, v8, v15, 1
	v_add_u32_e32 v15, 0x2000, v169
	v_lshlrev_b32_e32 v19, 1, v16
	v_lshrrev_b32_e32 v20, 2, v16
	v_and_or_b32 v18, v16, s12, v18
	v_lshl_add_u32 v158, v16, 11, v8
	v_ashrrev_i32_e32 v16, 31, v15
	v_lshrrev_b32_e32 v16, 22, v16
	v_and_b32_e32 v19, 24, v19
	v_and_b32_e32 v20, 4, v20
	v_add_u32_e32 v16, v15, v16
	v_or3_b32 v18, v18, v20, v19
	v_ashrrev_i32_e32 v16, 10, v16
	v_lshrrev_b32_e32 v250, 5, v18
	v_and_b32_e32 v251, 31, v18
	v_lshl_add_u32 v251, v250, 6, v251
	v_lshl_add_u32 v8, v251, 11, v8
	v_mul_i32_i24_e32 v18, 0x400, v16
	v_sub_u32_e32 v15, v15, v18
	v_lshrrev_b32_e32 v18, 4, v15
	v_bitop3_b32 v15, v18, v15, 32 bitop3:0x6c
	v_ashrrev_i32_e32 v19, 31, v15
	v_lshrrev_b32_e32 v19, 26, v19
	v_lshlrev_b32_e32 v18, 3, v16
	v_add_u32_e32 v19, v15, v19
	v_and_b32_e32 v18, -16, v18
	v_ashrrev_i32_e32 v20, 6, v19
	v_and_b32_e32 v19, 0xc0, v19
	s_addc_u32 s35, s44, s13
	v_add_u32_e32 v18, v20, v18
	v_sub_u32_e32 v15, v15, v19
	s_ashr_i32 s20, s17, 6
	v_lshlrev_b32_e32 v16, 5, v16
	v_ashrrev_i16_sdwa v15, v17, sext(v15) dst_sel:DWORD dst_unused:UNUSED_PAD src0_sel:DWORD src1_sel:BYTE_0
	v_lshlrev_b32_e32 v17, 1, v18
	v_lshrrev_b32_e32 v19, 2, v18
	v_and_b32_e32 v20, 3, v20
	s_lshl_b32 s27, s20, 10
	v_and_b32_e32 v16, 32, v16
	v_bfe_i32 v15, v15, 0, 16
	v_and_b32_e32 v17, 24, v17
	v_and_b32_e32 v19, 4, v19
	v_and_or_b32 v20, v18, s12, v20
	s_add_i32 s29, s27, 0
	v_or3_b32 v17, v20, v19, v17
	v_add_lshl_u32 v15, v16, v15, 1
	s_mov_b64 s[12:13], s[34:35]
	s_add_i32 m0, s29, 0x10000
	s_ashr_i32 s6, s17, 8
	v_lshrrev_b32_e32 v250, 5, v17
	v_and_b32_e32 v251, 31, v17
	v_lshl_add_u32 v251, v250, 6, v251
	v_lshl_add_u32 v162, v251, 11, v15
	v_lshl_add_u32 v160, v18, 11, v15
	global_load_lds_dwordx4 v8, s[12:13]
	s_add_i32 m0, s29, 0x12000
	v_mov_b32_e32 v163, v9
	global_load_lds_dwordx4 v162, s[12:13]
	s_add_u32 s12, s34, 0x10000
	s_addc_u32 s13, s35, 0
	s_add_i32 m0, s29, 0x14000
	s_add_i32 s45, s29, 0x2000
	global_load_lds_dwordx4 v8, s[12:13]
	s_add_i32 m0, s29, 0x16000
	v_mov_b32_e32 v159, v9
	global_load_lds_dwordx4 v162, s[12:13]
	s_mov_b64 s[12:13], s[8:9]
	s_mov_b32 m0, s29
	v_mov_b32_e32 v161, v9
	global_load_lds_dwordx4 v158, s[12:13]
	s_mov_b32 m0, s45
	s_nop 0
	global_load_lds_dwordx4 v160, s[12:13]
	s_add_u32 s12, s8, 0x40000
	s_addc_u32 s13, s9, 0
	s_add_i32 s46, s29, 0x4000
	s_mov_b32 m0, s46
	s_add_i32 s47, s29, 0x6000
	s_cmp_eq_u32 s6, 1
	global_load_lds_dwordx4 v158, s[12:13]
	s_mov_b32 m0, s47
	s_nop 0
	global_load_lds_dwordx4 v160, s[12:13]
	s_cselect_b64 s[12:13], -1, 0
	s_cmp_lg_u32 s6, 1
	s_cbranch_scc1 .LBB13_1064
	s_barrier
.LBB13_1064:
	s_mul_i32 s21, s7, s15
	s_sub_i32 s21, 0x8000, s21
	s_add_i32 s22, s7, 1
	s_sub_i32 s23, s21, s15
	s_cmp_ge_u32 s21, s15
	s_cselect_b32 s7, s22, s7
	s_cselect_b32 s21, s23, s21
	s_add_i32 s22, s7, 1
	s_cmp_ge_u32 s21, s15
	s_cselect_b32 s7, s22, s7
	s_xor_b32 s7, s7, s16
	s_sub_i32 s7, s7, s16
	s_mul_hi_i32 s15, s14, s7
	s_mul_i32 s14, s14, s7
	s_lshl_b64 s[14:15], s[14:15], 13
	s_add_u32 s7, s18, s14
	s_addc_u32 s16, s19, s15
	s_sub_u32 s14, 0, s14
	s_subb_u32 s15, 0, s15
	s_add_u32 s7, s7, s14
	s_addc_u32 s15, s16, s15
	s_add_u32 s14, s7, 0x8000000
	s_addc_u32 s15, s15, 0
	s_lshl_b32 s48, s6, 6
	s_lshl_b32 s16, s6, 13
	s_lshl_b32 s6, s20, 5
	s_and_b32 s49, s6, 0x60
	s_lshl_b32 s18, s49, 7
	s_add_u32 s6, s34, 0x80
	s_addc_u32 s7, s35, 0
	s_waitcnt vmcnt(2)
	s_barrier
	s_add_i32 m0, s29, 0x18000
	v_lshl_add_u64 v[16:17], s[6:7], 0, v[8:9]
	global_load_lds_dwordx4 v[16:17], off
	s_add_i32 m0, s29, 0x1a000
	v_lshl_add_u64 v[16:17], s[6:7], 0, v[162:163]
	s_add_u32 s6, s8, 0x80
	s_addc_u32 s7, s9, 0
	s_add_i32 s50, s29, 0x8000
	global_load_lds_dwordx4 v[16:17], off
	s_mov_b32 m0, s50
	v_lshl_add_u64 v[16:17], s[6:7], 0, v[158:159]
	s_add_i32 s51, s29, 0xa000
	global_load_lds_dwordx4 v[16:17], off
	v_lshl_add_u64 v[16:17], s[6:7], 0, v[160:161]
	s_add_u32 s6, s34, 0x10080
	s_mov_b32 m0, s51
	s_addc_u32 s7, s35, 0
	global_load_lds_dwordx4 v[16:17], off
	s_add_i32 m0, s29, 0x1c000
	v_lshl_add_u64 v[16:17], s[6:7], 0, v[8:9]
	global_load_lds_dwordx4 v[16:17], off
	v_lshl_add_u64 v[16:17], s[6:7], 0, v[162:163]
	s_add_i32 m0, s29, 0x1e000
	v_and_b32_e32 v9, 48, v14
	global_load_lds_dwordx4 v[16:17], off
	v_lshlrev_b32_e32 v15, 6, v14
	s_movk_i32 s6, 0x3c0
	v_and_or_b32 v9, v15, s6, v9
	v_lshlrev_b32_e32 v15, 2, v14
	v_and_b32_e32 v16, 32, v15
	v_bitop3_b32 v17, v9, s16, v16 bitop3:0xde
	s_add_i32 s16, 0, 0x21800
	v_add_u32_e32 v159, s16, v15
	s_add_i32 s16, 0, 0x22800
	s_waitcnt vmcnt(6)
	s_cmpk_lt_u32 s17, 0x100
	v_bitop3_b32 v9, s18, v9, v16 bitop3:0xf6
	v_and_b32_e32 v14, 1, v14
	v_add_u32_e32 v161, s16, v169
	s_cselect_b64 s[16:17], -1, 0
	s_add_i32 s18, 0, 0x21200
	s_add_i32 s53, 0, 0x10000
	s_add_i32 s54, 0, 0x14000
	s_mov_b32 s56, 0
	v_cmp_eq_u32_e64 s[6:7], 0, v14
	v_mov_b32_e32 v163, s18
	v_mov_b32_e32 v170, 0x358637bd
	s_mov_b32 s52, 0x800000
	v_add_u32_e32 v171, s53, v9
	v_add_u32_e32 v172, s54, v9
	v_add_u32_e32 v173, 0, v17
	s_barrier
	s_branch .LBB13_1067

; #define PG8_STAGE(bufoff, gbase, voff) do { const char* gb_ = (const char*)(gbase); asm volatile("" : "+s"(gb_));     \
;         _Pragma("unroll") for (int _i = 0; _i < 2; ++_i) \
;         __builtin_amdgcn_global_load_lds((const unsigned*)(gb_ + (voff)[_i]), (PG8_LAS unsigned*)(lds + (bufoff) + ldsw + _i * 8192), 16, 0, 0); } while (0)
; #define PG8_LDA(dst, b, h) do { _Pragma("unroll") for (int m = 0; m < 4; ++m) _Pragma("unroll") for (int k = 0; k < 2; ++k) dst[m][k] = *(const PG8_LAS bf16x8*)(lds + PG8_SA(b, h) + aoff + m * 2048 + k * 1024); } while (0)
; #define PG8_LDB(dst, b, h) do { _Pragma("unroll") for (int n = 0; n < 2; ++n) _Pragma("unroll") for (int k = 0; k < 2; ++k) dst[n][k] = *(const PG8_LAS bf16x8*)(lds + PG8_SB(b, h) + boff + n * 2048 + k * 1024); } while (0)
; #define PG8_MMA(ai, bj, At, Bt) do { __builtin_amdgcn_s_setprio(1); _Pragma("unroll") for (int m = 0; m < 4; ++m) _Pragma("unroll") for (int n = 0; n < 2; ++n) _Pragma("unroll") for (int k = 0; k < 2; ++k) \
;         acc[ai][bj][m][n] = __builtin_amdgcn_mfma_f32_16x16x32_bf16(Bt[n][k], At[m][k], acc[ai][bj][m][n], 0, 0, 0); __builtin_amdgcn_s_setprio(0); } while (0)
; #define PG8_WAIT_V(n) asm volatile("s_waitcnt vmcnt(" #n ")" ::: "memory")
; #define PG8_WAIT_L(n) asm volatile("s_waitcnt lgkmcnt(" #n ")" ::: "memory")
; #define PG8_BAR __builtin_amdgcn_s_barrier()
; #define PG8_SCHED __builtin_amdgcn_sched_barrier(0)
; template <class Epi, class Sched, bool ALIGN_EPI = false, bool SP2 = false>
; __device__ __forceinline__ void gemm_phase(PG8_LAS unsigned char* lds, const Gemm g, const Sched& S, const Epi& E, int wid0) {
;     ...
;             PG8_LDB(B0, 0, 0); PG8_LDB(B1, 0, 1); PG8_SCHED; PG8_LDA(At, 0, 0); PG8_STAGE(PG8_SA(1, 1), a1 + hstepA, vA_);
;             PG8_WAIT_V(8); PG8_WAIT_L(0); PG8_BAR; PG8_MMA(0, 0, At, B0); PG8_MMA(0, 1, At, B1); PG8_BAR; PG8_SCHED;
;             PG8_LDA(At, 0, 1); PG8_STAGE(PG8_SB(0, 0), b2, vB_); PG8_STAGE(PG8_SB(0, 1), b2 + hstep, vB_); PG8_STAGE(PG8_SA(0, 0), a2, vA_);
;             PG8_WAIT_V(8); PG8_WAIT_L(0); PG8_BAR; PG8_MMA(1, 0, At, B0); PG8_MMA(1, 1, At, B1); PG8_BAR; PG8_SCHED;
.Lff1a_wd_0:
	s_waitcnt lgkmcnt(0)
	s_barrier
	s_setprio 1
	s_waitcnt lgkmcnt(0)
	v_mfma_f32_16x16x32_bf16 v[138:141], v[142:145], v[186:189], v[138:141]
	v_mfma_f32_16x16x32_bf16 v[134:137], v[150:153], v[186:189], v[134:137]
	v_mfma_f32_16x16x32_bf16 v[122:125], v[142:145], v[194:197], v[122:125]
	v_mfma_f32_16x16x32_bf16 v[118:121], v[150:153], v[194:197], v[118:121]
	v_mfma_f32_16x16x32_bf16 v[106:109], v[142:145], v[202:205], v[106:109]
	v_mfma_f32_16x16x32_bf16 v[102:105], v[150:153], v[202:205], v[102:105]
	v_mfma_f32_16x16x32_bf16 v[90:93], v[142:145], v[210:213], v[90:93]
	v_mfma_f32_16x16x32_bf16 v[86:89], v[150:153], v[210:213], v[86:89]
	v_mfma_f32_16x16x32_bf16 v[138:141], v[146:149], v[190:193], v[138:141]
	v_mfma_f32_16x16x32_bf16 v[134:137], v[154:157], v[190:193], v[134:137]
	v_mfma_f32_16x16x32_bf16 v[122:125], v[146:149], v[198:201], v[122:125]
	v_mfma_f32_16x16x32_bf16 v[118:121], v[154:157], v[198:201], v[118:121]
	v_mfma_f32_16x16x32_bf16 v[106:109], v[146:149], v[206:209], v[106:109]
	v_mfma_f32_16x16x32_bf16 v[102:105], v[154:157], v[206:209], v[102:105]
	v_mfma_f32_16x16x32_bf16 v[90:93], v[146:149], v[214:217], v[90:93]
	v_mfma_f32_16x16x32_bf16 v[86:89], v[154:157], v[214:217], v[86:89]
	s_setprio 0
	s_setprio 1
	v_mfma_f32_16x16x32_bf16 v[130:133], v[164:167], v[186:189], v[130:133]
	v_mfma_f32_16x16x32_bf16 v[126:129], v[178:181], v[186:189], v[126:129]
	v_mfma_f32_16x16x32_bf16 v[114:117], v[164:167], v[194:197], v[114:117]
	v_mfma_f32_16x16x32_bf16 v[110:113], v[178:181], v[194:197], v[110:113]
	v_mfma_f32_16x16x32_bf16 v[98:101], v[164:167], v[202:205], v[98:101]
	v_mfma_f32_16x16x32_bf16 v[94:97], v[178:181], v[202:205], v[94:97]
	v_mfma_f32_16x16x32_bf16 v[82:85], v[164:167], v[210:213], v[82:85]
	v_mfma_f32_16x16x32_bf16 v[78:81], v[178:181], v[210:213], v[78:81]
	v_mfma_f32_16x16x32_bf16 v[130:133], v[174:177], v[190:193], v[130:133]
	v_mfma_f32_16x16x32_bf16 v[126:129], v[182:185], v[190:193], v[126:129]
	v_mfma_f32_16x16x32_bf16 v[114:117], v[174:177], v[198:201], v[114:117]
	v_mfma_f32_16x16x32_bf16 v[110:113], v[182:185], v[198:201], v[110:113]
	v_mfma_f32_16x16x32_bf16 v[98:101], v[174:177], v[206:209], v[98:101]
	v_mfma_f32_16x16x32_bf16 v[94:97], v[182:185], v[206:209], v[94:97]
	v_mfma_f32_16x16x32_bf16 v[82:85], v[174:177], v[214:217], v[82:85]
	v_mfma_f32_16x16x32_bf16 v[78:81], v[182:185], v[214:217], v[78:81]
	s_setprio 0
	s_barrier
	s_add_i32 s62, s53, s27
	s_mov_b64 s[8:9], s[38:39]
	s_mov_b32 m0, s62
	ds_read_b128 v[186:189], v173 offset:16384
	ds_read_b128 v[190:193], v173 offset:17408
	ds_read_b128 v[194:197], v173 offset:18432
	ds_read_b128 v[198:201], v173 offset:19456
	ds_read_b128 v[202:205], v173 offset:20480
	ds_read_b128 v[206:209], v173 offset:21504
	ds_read_b128 v[210:213], v173 offset:22528
	ds_read_b128 v[214:217], v173 offset:23552
	s_nop 0
	global_load_lds_dwordx4 v219, s[8:9]
	s_add_i32 m0, s62, 0x2000
	s_nop 0
	global_load_lds_dwordx4 v221, s[8:9]
	s_add_u32 s8, s38, 0x10000
	s_addc_u32 s9, s39, 0
	s_add_i32 s62, s54, s27
	s_mov_b32 m0, s62
	s_nop 0
	global_load_lds_dwordx4 v219, s[8:9]
	s_add_i32 m0, s62, 0x2000
	s_nop 0
	global_load_lds_dwordx4 v221, s[8:9]
	s_mov_b64 s[8:9], s[40:41]
	s_mov_b32 m0, s29
	s_nop 0
	global_load_lds_dwordx4 v218, s[8:9]
	s_mov_b32 m0, s45
	s_nop 0
	global_load_lds_dwordx4 v220, s[8:9]
	s_cmp_lg_u32 s61, -2
	s_cbranch_scc1 .Lff1a_w8_1
	s_cmp_eq_u32 s56, 0
	s_cbranch_scc1 .Lff1a_w8_1
	s_waitcnt vmcnt(24)
	s_branch .Lff1a_wd_1

; #define PG8_STAGE(bufoff, gbase, voff) do { const char* gb_ = (const char*)(gbase); asm volatile("" : "+s"(gb_));     \
;         _Pragma("unroll") for (int _i = 0; _i < 2; ++_i) \
;         __builtin_amdgcn_global_load_lds((const unsigned*)(gb_ + (voff)[_i]), (PG8_LAS unsigned*)(lds + (bufoff) + ldsw + _i * 8192), 16, 0, 0); } while (0)
; #define PG8_LDA(dst, b, h) do { _Pragma("unroll") for (int m = 0; m < 4; ++m) _Pragma("unroll") for (int k = 0; k < 2; ++k) dst[m][k] = *(const PG8_LAS bf16x8*)(lds + PG8_SA(b, h) + aoff + m * 2048 + k * 1024); } while (0)
; #define PG8_LDB(dst, b, h) do { _Pragma("unroll") for (int n = 0; n < 2; ++n) _Pragma("unroll") for (int k = 0; k < 2; ++k) dst[n][k] = *(const PG8_LAS bf16x8*)(lds + PG8_SB(b, h) + boff + n * 2048 + k * 1024); } while (0)
; #define PG8_MMA(ai, bj, At, Bt) do { __builtin_amdgcn_s_setprio(1); _Pragma("unroll") for (int m = 0; m < 4; ++m) _Pragma("unroll") for (int n = 0; n < 2; ++n) _Pragma("unroll") for (int k = 0; k < 2; ++k) \
;         acc[ai][bj][m][n] = __builtin_amdgcn_mfma_f32_16x16x32_bf16(Bt[n][k], At[m][k], acc[ai][bj][m][n], 0, 0, 0); __builtin_amdgcn_s_setprio(0); } while (0)
; #define PG8_WAIT_V(n) asm volatile("s_waitcnt vmcnt(" #n ")" ::: "memory")
; #define PG8_WAIT_L(n) asm volatile("s_waitcnt lgkmcnt(" #n ")" ::: "memory")
; #define PG8_BAR __builtin_amdgcn_s_barrier()
; #define PG8_SCHED __builtin_amdgcn_sched_barrier(0)
; template <class Epi, class Sched, bool ALIGN_EPI = false, bool SP2 = false>
; __device__ __forceinline__ void gemm_phase(PG8_LAS unsigned char* lds, const Gemm g, const Sched& S, const Epi& E, int wid0) {
;     ...
;             PG8_WAIT_V(8); PG8_WAIT_L(0); PG8_BAR; PG8_MMA(1, 0, At, B0); PG8_MMA(1, 1, At, B1); PG8_BAR; PG8_SCHED;
;             PG8_LDB(B0, 1, 0); PG8_LDB(B1, 1, 1); PG8_SCHED; PG8_LDA(At, 1, 0); PG8_STAGE(PG8_SA(0, 1), a2 + hstepA, vA_);
;             PG8_WAIT_V(8); PG8_WAIT_L(0); PG8_BAR; PG8_MMA(0, 0, At, B0); PG8_MMA(0, 1, At, B1); PG8_BAR; PG8_SCHED;
.Lff1a_wd_1:
	s_waitcnt lgkmcnt(0)
	s_barrier
	s_setprio 1
	s_waitcnt lgkmcnt(0)
	v_mfma_f32_16x16x32_bf16 v[74:77], v[142:145], v[186:189], v[74:77]
	v_mfma_f32_16x16x32_bf16 v[70:73], v[150:153], v[186:189], v[70:73]
	v_mfma_f32_16x16x32_bf16 v[58:61], v[142:145], v[194:197], v[58:61]
	v_mfma_f32_16x16x32_bf16 v[54:57], v[150:153], v[194:197], v[54:57]
	v_mfma_f32_16x16x32_bf16 v[42:45], v[142:145], v[202:205], v[42:45]
	v_mfma_f32_16x16x32_bf16 v[38:41], v[150:153], v[202:205], v[38:41]
	v_mfma_f32_16x16x32_bf16 v[26:29], v[142:145], v[210:213], v[26:29]
	v_mfma_f32_16x16x32_bf16 v[22:25], v[150:153], v[210:213], v[22:25]
	v_mfma_f32_16x16x32_bf16 v[74:77], v[146:149], v[190:193], v[74:77]
	v_mfma_f32_16x16x32_bf16 v[70:73], v[154:157], v[190:193], v[70:73]
	v_mfma_f32_16x16x32_bf16 v[58:61], v[146:149], v[198:201], v[58:61]
	v_mfma_f32_16x16x32_bf16 v[54:57], v[154:157], v[198:201], v[54:57]
	v_mfma_f32_16x16x32_bf16 v[42:45], v[146:149], v[206:209], v[42:45]
	v_mfma_f32_16x16x32_bf16 v[38:41], v[154:157], v[206:209], v[38:41]
	v_mfma_f32_16x16x32_bf16 v[26:29], v[146:149], v[214:217], v[26:29]
	v_mfma_f32_16x16x32_bf16 v[22:25], v[154:157], v[214:217], v[22:25]
	s_setprio 0
	s_setprio 1
	v_mfma_f32_16x16x32_bf16 v[66:69], v[164:167], v[186:189], v[66:69]
	v_mfma_f32_16x16x32_bf16 v[62:65], v[178:181], v[186:189], v[62:65]
	v_mfma_f32_16x16x32_bf16 v[50:53], v[164:167], v[194:197], v[50:53]
	v_mfma_f32_16x16x32_bf16 v[46:49], v[178:181], v[194:197], v[46:49]
	v_mfma_f32_16x16x32_bf16 v[34:37], v[164:167], v[202:205], v[34:37]
	v_mfma_f32_16x16x32_bf16 v[30:33], v[178:181], v[202:205], v[30:33]
	v_mfma_f32_16x16x32_bf16 v[18:21], v[164:167], v[210:213], v[18:21]
	v_mfma_f32_16x16x32_bf16 v[14:17], v[178:181], v[210:213], v[14:17]
	v_mfma_f32_16x16x32_bf16 v[66:69], v[174:177], v[190:193], v[66:69]
	v_mfma_f32_16x16x32_bf16 v[62:65], v[182:185], v[190:193], v[62:65]
	v_mfma_f32_16x16x32_bf16 v[50:53], v[174:177], v[198:201], v[50:53]
	v_mfma_f32_16x16x32_bf16 v[46:49], v[182:185], v[198:201], v[46:49]
	v_mfma_f32_16x16x32_bf16 v[34:37], v[174:177], v[206:209], v[34:37]
	v_mfma_f32_16x16x32_bf16 v[30:33], v[182:185], v[206:209], v[30:33]
	v_mfma_f32_16x16x32_bf16 v[18:21], v[174:177], v[214:217], v[18:21]
	v_mfma_f32_16x16x32_bf16 v[14:17], v[182:185], v[214:217], v[14:17]
	s_setprio 0
	s_barrier
	s_add_i32 s62, 0, 0x18000
	s_add_i32 s63, 0, 0x1c000
	v_add_u32_e32 v154, s62, v9
	v_add_u32_e32 v182, s63, v9
	ds_read_b128 v[142:145], v154
	ds_read_b128 v[146:149], v154 offset:1024
	ds_read_b128 v[150:153], v154 offset:2048
	ds_read_b128 v[154:157], v154 offset:3072
	ds_read_b128 v[164:167], v182
	ds_read_b128 v[174:177], v182 offset:1024
	ds_read_b128 v[178:181], v182 offset:2048
	ds_read_b128 v[182:185], v182 offset:3072
	s_add_u32 s8, s40, 0x40000
	s_addc_u32 s9, s41, 0
	s_mov_b32 m0, s46
	ds_read_b128 v[186:189], v173 offset:32768
	ds_read_b128 v[190:193], v173 offset:33792
	ds_read_b128 v[194:197], v173 offset:34816
	ds_read_b128 v[198:201], v173 offset:35840
	ds_read_b128 v[202:205], v173 offset:36864
	ds_read_b128 v[206:209], v173 offset:37888
	ds_read_b128 v[210:213], v173 offset:38912
	ds_read_b128 v[214:217], v173 offset:39936
	s_nop 0
	global_load_lds_dwordx4 v218, s[8:9]
	s_mov_b32 m0, s47
	s_nop 0
	global_load_lds_dwordx4 v220, s[8:9]
	s_waitcnt vmcnt(8)
	s_waitcnt lgkmcnt(0)
	s_barrier
	s_setprio 1
	s_waitcnt lgkmcnt(0)
	v_mfma_f32_16x16x32_bf16 v[138:141], v[142:145], v[186:189], v[138:141]
	v_mfma_f32_16x16x32_bf16 v[134:137], v[150:153], v[186:189], v[134:137]
	v_mfma_f32_16x16x32_bf16 v[122:125], v[142:145], v[194:197], v[122:125]
	v_mfma_f32_16x16x32_bf16 v[118:121], v[150:153], v[194:197], v[118:121]
	v_mfma_f32_16x16x32_bf16 v[106:109], v[142:145], v[202:205], v[106:109]
	v_mfma_f32_16x16x32_bf16 v[102:105], v[150:153], v[202:205], v[102:105]
	v_mfma_f32_16x16x32_bf16 v[90:93], v[142:145], v[210:213], v[90:93]
	v_mfma_f32_16x16x32_bf16 v[86:89], v[150:153], v[210:213], v[86:89]
	v_mfma_f32_16x16x32_bf16 v[138:141], v[146:149], v[190:193], v[138:141]
	v_mfma_f32_16x16x32_bf16 v[134:137], v[154:157], v[190:193], v[134:137]
	v_mfma_f32_16x16x32_bf16 v[122:125], v[146:149], v[198:201], v[122:125]
	v_mfma_f32_16x16x32_bf16 v[118:121], v[154:157], v[198:201], v[118:121]
	v_mfma_f32_16x16x32_bf16 v[106:109], v[146:149], v[206:209], v[106:109]
	v_mfma_f32_16x16x32_bf16 v[102:105], v[154:157], v[206:209], v[102:105]
	v_mfma_f32_16x16x32_bf16 v[90:93], v[146:149], v[214:217], v[90:93]
	v_mfma_f32_16x16x32_bf16 v[86:89], v[154:157], v[214:217], v[86:89]
	s_setprio 0
	s_setprio 1
	v_mfma_f32_16x16x32_bf16 v[130:133], v[164:167], v[186:189], v[130:133]
	v_mfma_f32_16x16x32_bf16 v[126:129], v[178:181], v[186:189], v[126:129]
	v_mfma_f32_16x16x32_bf16 v[114:117], v[164:167], v[194:197], v[114:117]
	v_mfma_f32_16x16x32_bf16 v[110:113], v[178:181], v[194:197], v[110:113]
	v_mfma_f32_16x16x32_bf16 v[98:101], v[164:167], v[202:205], v[98:101]
	v_mfma_f32_16x16x32_bf16 v[94:97], v[178:181], v[202:205], v[94:97]
	v_mfma_f32_16x16x32_bf16 v[82:85], v[164:167], v[210:213], v[82:85]
	v_mfma_f32_16x16x32_bf16 v[78:81], v[178:181], v[210:213], v[78:81]
	v_mfma_f32_16x16x32_bf16 v[130:133], v[174:177], v[190:193], v[130:133]
	v_mfma_f32_16x16x32_bf16 v[126:129], v[182:185], v[190:193], v[126:129]
	v_mfma_f32_16x16x32_bf16 v[114:117], v[174:177], v[198:201], v[114:117]
	v_mfma_f32_16x16x32_bf16 v[110:113], v[182:185], v[198:201], v[110:113]
	v_mfma_f32_16x16x32_bf16 v[98:101], v[174:177], v[206:209], v[98:101]
	v_mfma_f32_16x16x32_bf16 v[94:97], v[182:185], v[206:209], v[94:97]
	v_mfma_f32_16x16x32_bf16 v[82:85], v[174:177], v[214:217], v[82:85]
	v_mfma_f32_16x16x32_bf16 v[78:81], v[182:185], v[214:217], v[78:81]
	s_setprio 0
	s_barrier
; #define PG8_STAGE(bufoff, gbase, voff) do { const char* gb_ = (const char*)(gbase); asm volatile("" : "+s"(gb_));     \
;         _Pragma("unroll") for (int _i = 0; _i < 2; ++_i) \
;         __builtin_amdgcn_global_load_lds((const unsigned*)(gb_ + (voff)[_i]), (PG8_LAS unsigned*)(lds + (bufoff) + ldsw + _i * 8192), 16, 0, 0); } while (0)
; #define PG8_LDA(dst, b, h) do { _Pragma("unroll") for (int m = 0; m < 4; ++m) _Pragma("unroll") for (int k = 0; k < 2; ++k) dst[m][k] = *(const PG8_LAS bf16x8*)(lds + PG8_SA(b, h) + aoff + m * 2048 + k * 1024); } while (0)
; #define PG8_MMA(ai, bj, At, Bt) do { __builtin_amdgcn_s_setprio(1); _Pragma("unroll") for (int m = 0; m < 4; ++m) _Pragma("unroll") for (int n = 0; n < 2; ++n) _Pragma("unroll") for (int k = 0; k < 2; ++k) \
;         acc[ai][bj][m][n] = __builtin_amdgcn_mfma_f32_16x16x32_bf16(Bt[n][k], At[m][k], acc[ai][bj][m][n], 0, 0, 0); __builtin_amdgcn_s_setprio(0); } while (0)
; #define PG8_WAIT_V(n) asm volatile("s_waitcnt vmcnt(" #n ")" ::: "memory")
; #define PG8_WAIT_L(n) asm volatile("s_waitcnt lgkmcnt(" #n ")" ::: "memory")
; #define PG8_BAR __builtin_amdgcn_s_barrier()
; #define PG8_SCHED __builtin_amdgcn_sched_barrier(0)
; template <class Epi, class Sched, bool ALIGN_EPI = false, bool SP2 = false>
; __device__ __forceinline__ void gemm_phase(PG8_LAS unsigned char* lds, const Gemm g, const Sched& S, const Epi& E, int wid0) {
;     ...
;         for (int t = 0; t < nt; t += 2) {
;     ...
;             PG8_LDA(At, 1, 1); PG8_STAGE(PG8_SB(1, 0), b3, vB_); PG8_STAGE(PG8_SB(1, 1), b3 + hstep, vB_); PG8_STAGE(PG8_SA(1, 0), a3, vA_);
;             PG8_WAIT_V(8); PG8_WAIT_L(0); PG8_BAR; PG8_MMA(1, 0, At, B0); PG8_MMA(1, 1, At, B1); PG8_BAR; PG8_SCHED;
	s_add_u32 s8, s38, 0x80
	s_addc_u32 s9, s39, 0
	s_add_i32 s40, s62, s27
	s_mov_b32 m0, s40
	ds_read_b128 v[186:189], v173 offset:49152
	ds_read_b128 v[190:193], v173 offset:50176
	ds_read_b128 v[194:197], v173 offset:51200
	ds_read_b128 v[198:201], v173 offset:52224
	ds_read_b128 v[202:205], v173 offset:53248
	ds_read_b128 v[206:209], v173 offset:54272
	ds_read_b128 v[210:213], v173 offset:55296
	ds_read_b128 v[214:217], v173 offset:56320
	s_nop 0
	global_load_lds_dwordx4 v219, s[8:9]
	s_add_i32 m0, s40, 0x2000
	s_nop 0
	global_load_lds_dwordx4 v221, s[8:9]
	s_add_u32 s8, s38, 0x10080
	s_addc_u32 s9, s39, 0
	s_add_i32 s38, s63, s27
	s_mov_b32 m0, s38
	s_nop 0
	global_load_lds_dwordx4 v219, s[8:9]
	s_add_i32 m0, s38, 0x2000
	s_nop 0
	global_load_lds_dwordx4 v221, s[8:9]
	s_mov_b32 m0, s50
	s_nop 0
	global_load_lds_dwordx4 v218, s[36:37]
	s_mov_b32 m0, s51
	s_nop 0
	global_load_lds_dwordx4 v220, s[36:37]
	s_waitcnt vmcnt(8)
	s_waitcnt lgkmcnt(0)
	s_barrier
	s_setprio 1
	s_waitcnt lgkmcnt(0)
	v_mfma_f32_16x16x32_bf16 v[74:77], v[142:145], v[186:189], v[74:77]
	v_mfma_f32_16x16x32_bf16 v[70:73], v[150:153], v[186:189], v[70:73]
	v_mfma_f32_16x16x32_bf16 v[58:61], v[142:145], v[194:197], v[58:61]
	v_mfma_f32_16x16x32_bf16 v[54:57], v[150:153], v[194:197], v[54:57]
	v_mfma_f32_16x16x32_bf16 v[42:45], v[142:145], v[202:205], v[42:45]
	v_mfma_f32_16x16x32_bf16 v[38:41], v[150:153], v[202:205], v[38:41]
	v_mfma_f32_16x16x32_bf16 v[26:29], v[142:145], v[210:213], v[26:29]
	v_mfma_f32_16x16x32_bf16 v[22:25], v[150:153], v[210:213], v[22:25]
	v_mfma_f32_16x16x32_bf16 v[74:77], v[146:149], v[190:193], v[74:77]
	v_mfma_f32_16x16x32_bf16 v[70:73], v[154:157], v[190:193], v[70:73]
	v_mfma_f32_16x16x32_bf16 v[58:61], v[146:149], v[198:201], v[58:61]
	v_mfma_f32_16x16x32_bf16 v[54:57], v[154:157], v[198:201], v[54:57]
	v_mfma_f32_16x16x32_bf16 v[42:45], v[146:149], v[206:209], v[42:45]
	v_mfma_f32_16x16x32_bf16 v[38:41], v[154:157], v[206:209], v[38:41]
	v_mfma_f32_16x16x32_bf16 v[26:29], v[146:149], v[214:217], v[26:29]
	v_mfma_f32_16x16x32_bf16 v[22:25], v[154:157], v[214:217], v[22:25]
	s_setprio 0
	s_setprio 1
	v_mfma_f32_16x16x32_bf16 v[66:69], v[164:167], v[186:189], v[66:69]
	v_mfma_f32_16x16x32_bf16 v[62:65], v[178:181], v[186:189], v[62:65]
	v_mfma_f32_16x16x32_bf16 v[50:53], v[164:167], v[194:197], v[50:53]
	v_mfma_f32_16x16x32_bf16 v[46:49], v[178:181], v[194:197], v[46:49]
	v_mfma_f32_16x16x32_bf16 v[34:37], v[164:167], v[202:205], v[34:37]
	v_mfma_f32_16x16x32_bf16 v[30:33], v[178:181], v[202:205], v[30:33]
	v_mfma_f32_16x16x32_bf16 v[18:21], v[164:167], v[210:213], v[18:21]
	v_mfma_f32_16x16x32_bf16 v[14:17], v[178:181], v[210:213], v[14:17]
	v_mfma_f32_16x16x32_bf16 v[66:69], v[174:177], v[190:193], v[66:69]
	v_mfma_f32_16x16x32_bf16 v[62:65], v[182:185], v[190:193], v[62:65]
	v_mfma_f32_16x16x32_bf16 v[50:53], v[174:177], v[198:201], v[50:53]
	v_mfma_f32_16x16x32_bf16 v[46:49], v[182:185], v[198:201], v[46:49]
	v_mfma_f32_16x16x32_bf16 v[34:37], v[174:177], v[206:209], v[34:37]
	v_mfma_f32_16x16x32_bf16 v[30:33], v[182:185], v[206:209], v[30:33]
	v_mfma_f32_16x16x32_bf16 v[18:21], v[174:177], v[214:217], v[18:21]
	v_mfma_f32_16x16x32_bf16 v[14:17], v[182:185], v[214:217], v[14:17]
	s_setprio 0
	s_barrier
	s_add_i32 s61, s61, 2
	s_add_u32 s59, s59, 0x100
	s_addc_u32 s60, s60, 0
	s_cmp_gt_u32 s61, 13
	s_mov_b64 s[8:9], s[34:35]
	s_cbranch_scc0 .LBB13_1074
	s_and_b64 vcc, exec, s[16:17]
	s_cbranch_vccz .LBB13_1077
	s_barrier

; __device__ __forceinline__ int lane_id() { int l; asm volatile("v_mbcnt_lo_u32_b32 %0, -1, 0\n\tv_mbcnt_hi_u32_b32 %0, -1, %0" : "=v"(l)); return l; }
; __device__ __forceinline__ u32x4 pack8(const f32x4& a, const f32x4& b) { u32x4 w; w.x = cvt_pk_bf16(a[0], a[1]); w.y = cvt_pk_bf16(a[2], a[3]); w.z = cvt_pk_bf16(b[0], b[1]); w.w = cvt_pk_bf16(b[2], b[3]); return w; }
; #define PG8_SH_LDS(sh) do { PG8_LAS const unsigned char* sq_ = slds + RSTAT_OFF + 4096 + (u.ui & 1) * 1024 + (wc * 32 + 8 * fq) * 4; \
;     _Pragma("unroll") for (int bj = 0; bj < 2; ++bj) _Pragma("unroll") for (int n = 0; n < 2; ++n) sh[bj][n] = *(PG8_LAS const f32x4*)(sq_ + (bj * HALF + 4 * n) * 4); } while (0)
; #define PG8_RSTD8_LDS(rsv) do { PG8_LAS const unsigned char* sp_ = slds + RSTAT_OFF + (u.ui & 1) * 2048 + (wr * 64 + fr) * 8; \
;     _Pragma("unroll") for (int ai = 0; ai < 2; ++ai) _Pragma("unroll") for (int m = 0; m < 4; ++m) rsv[ai][m] = *(PG8_LAS const float*)(sp_ + (ai * 128 + m * 16) * 8); } while (0)
;     __device__ __forceinline__ void operator()(const f32x4 (&acc)[2][2][4][2], const Unit& u, int wr, int wc, int fr, int fq) const {
;         { const int l_ = lane_id(); fr = l_ & 15; fq = l_ >> 4; }
;         const int b = u.pm >> 3, c0 = u.pn * BM + wc * 32 + 8 * fq;
;         f32x4 sh[2][2]; PG8_SH_LDS(sh);
;         float rsv[2][4]; PG8_RSTD8_LDS(rsv);
; #pragma unroll
;         for (int ai = 0; ai < 2; ++ai)
; #pragma unroll
;             for (int m = 0; m < 4; ++m) { const int row = PG8_ROW(u, ai, m); const float rs = rsv[ai][m];
; #pragma unroll
;                 for (int bj = 0; bj < 2; ++bj) { f32x4 v0 = acc[ai][bj][m][0] * rs + sh[bj][0], v1 = acc[ai][bj][m][1] * rs + sh[bj][1];
; #pragma unroll
;                     for (int i = 0; i < 4; ++i) { const float a = fmaxf(v0[i], 0.f), c = fmaxf(v1[i], 0.f); v0[i] = a * a; v1[i] = c * c; }
;                     stb(H, (unsigned)((row * DFF + c0 + bj * HALF) * 2), pack8(v0, v1)); } }
;     }
.LBB13_1081:
	v_mbcnt_lo_u32_b32 v164, -1, 0
	v_mbcnt_hi_u32_b32 v164, -1, v164
	s_lshl_b32 s98, s49, 1
	v_lshrrev_b32_e32 v250, 3, v164
	v_and_b32_e32 v250, 1, v250
	v_mul_i32_i24_e32 v251, 0xffff0040, v250
	v_add_u32_e32 v251, s98, v251
	s_lshl_b32 s19, s56, 10
	v_ashrrev_i32_e32 v142, 1, v164
	s_lshl_b32 s21, s56, 11
	v_and_b32_e32 v174, -8, v142
	s_and_b32 s19, s19, 0x400
	s_and_b32 s21, s21, 0x800
	s_add_i32 s19, s19, 0
	v_add_u32_e32 v142, s98, v174
	s_add_i32 s21, s21, 0
	v_and_or_b32 v175, v164, 15, s48
	v_lshl_add_u32 v142, v142, 2, s19
	v_lshl_add_u32 v164, v175, 3, s21
	v_add_u32_e32 v142, 0x22800, v142
	v_add_u32_e32 v164, 0x21800, v164
	ds_read_b128 v[154:157], v142
	ds_read_b128 v[150:153], v142 offset:16
	ds_read_b128 v[146:149], v142 offset:128
	ds_read_b128 v[142:145], v142 offset:144
	ds_read2_b32 v[176:177], v164 offset1:32
	ds_read2_b32 v[178:179], v164 offset0:64 offset1:96
	s_lshl_b32 s19, s28, 8
	s_or_b32 s19, s19, s49
	v_add_lshl_u32 v174, s19, v174, 1
	s_waitcnt lgkmcnt(0)
	v_pk_fma_f32 v[134:135], v[134:135], v[176:177], v[150:151] op_sel_hi:[1,0,1]
	s_lshl_b32 s19, s26, 21
	v_lshlrev_b32_e32 v175, 13, v175
	v_pk_fma_f32 v[138:139], v[138:139], v[176:177], v[154:155] op_sel_hi:[1,0,1]
	v_pk_fma_f32 v[136:137], v[136:137], v[176:177], v[152:153] op_sel_hi:[1,0,1]
	v_max_f32_e32 v134, 0, v134
	v_add3_u32 v174, v175, s19, v174
	v_pk_fma_f32 v[140:141], v[140:141], v[176:177], v[156:157] op_sel_hi:[1,0,1]
	v_mul_f32_e32 v175, v134, v134
	v_max_f32_e32 v134, 0, v139
	v_max_f32_e32 v135, 0, v135
	v_max_f32_e32 v136, 0, v136
	v_add_u32_e32 v164, 0x400, v164
	v_max_f32_e32 v138, 0, v138
	v_mul_f32_e32 v134, v134, v134
	v_mul_f32_e32 v139, v135, v135
	v_max_f32_e32 v135, 0, v140
	v_mul_f32_e32 v140, v136, v136
	v_max_f32_e32 v136, 0, v141
	v_max_f32_e32 v137, 0, v137
	v_pk_fma_f32 v[126:127], v[126:127], v[176:177], v[142:143] op_sel_hi:[1,0,1]
	ds_read2_b32 v[166:167], v164 offset1:32
	ds_read2_b32 v[164:165], v164 offset0:64 offset1:96
	v_mul_f32_e32 v138, v138, v138
	v_mul_f32_e32 v135, v135, v135
	v_mul_f32_e32 v136, v136, v136
	v_mul_f32_e32 v137, v137, v137
	v_cvt_pk_bf16_f32 v134, v138, v134
	v_pk_fma_f32 v[132:133], v[132:133], v[176:177], v[148:149] op_sel_hi:[1,0,1]
	v_pk_fma_f32 v[130:131], v[130:131], v[176:177], v[146:147] op_sel_hi:[1,0,1]
	v_pk_fma_f32 v[128:129], v[128:129], v[176:177], v[144:145] op_sel_hi:[1,0,1]
	v_max_f32_e32 v126, 0, v126
	v_max_f32_e32 v127, 0, v127
	v_cvt_pk_bf16_f32 v135, v135, v136
	v_cvt_pk_bf16_f32 v136, v175, v139
	v_cvt_pk_bf16_f32 v137, v140, v137
	v_mov_b32_e32 v232, v134
	v_mov_b32_e32 v233, v135
	v_mov_b32_e32 v234, v136
	v_mov_b32_e32 v235, v137
	v_add_u32_e32 v226, v174, v251
	v_max_f32_e32 v128, 0, v128
	v_max_f32_e32 v130, 0, v130
	v_mul_f32_e32 v134, v126, v126
	v_max_f32_e32 v126, 0, v131
	v_mul_f32_e32 v131, v127, v127
	v_max_f32_e32 v127, 0, v132
	v_mul_f32_e32 v126, v126, v126
	v_mul_f32_e32 v127, v127, v127
	v_mul_f32_e32 v132, v128, v128
	v_max_f32_e32 v128, 0, v133
	v_max_f32_e32 v129, 0, v129
	v_mul_f32_e32 v130, v130, v130
	v_mul_f32_e32 v128, v128, v128
	v_mul_f32_e32 v129, v129, v129
	v_add_u32_e32 v133, 0x100, v174
	v_cvt_pk_bf16_f32 v126, v130, v126
	v_cvt_pk_bf16_f32 v127, v127, v128
	v_cvt_pk_bf16_f32 v128, v134, v131
	v_cvt_pk_bf16_f32 v129, v132, v129
	v_mov_b32_e32 v240, v126
	v_mov_b32_e32 v241, v127
	v_mov_b32_e32 v242, v128
	v_mov_b32_e32 v243, v129
	s_nop 1
	v_mov_b32_dpp v240, v232 row_ror:8 row_mask:0xf bank_mask:0x3
	v_mov_b32_dpp v241, v233 row_ror:8 row_mask:0xf bank_mask:0x3
	v_mov_b32_dpp v242, v234 row_ror:8 row_mask:0xf bank_mask:0x3
	v_mov_b32_dpp v243, v235 row_ror:8 row_mask:0xf bank_mask:0x3
	v_mov_b32_dpp v232, v126 row_ror:8 row_mask:0xf bank_mask:0xc
	v_mov_b32_dpp v233, v127 row_ror:8 row_mask:0xf bank_mask:0xc
	v_mov_b32_dpp v234, v128 row_ror:8 row_mask:0xf bank_mask:0xc
	v_mov_b32_dpp v235, v129 row_ror:8 row_mask:0xf bank_mask:0xc
	global_store_dwordx4 v226, v[232:235], s[14:15]
	v_add_u32_e32 v248, 0x10000, v226
	global_store_dwordx4 v248, v[240:243], s[14:15]
	v_pk_fma_f32 v[102:103], v[102:103], v[178:179], v[150:151] op_sel_hi:[1,0,1]
	v_pk_fma_f32 v[106:107], v[106:107], v[178:179], v[154:155] op_sel_hi:[1,0,1]
	v_add_u32_e32 v127, 0x20000, v174
	v_mov_b32_e32 v126, v177
	v_pk_fma_f32 v[118:119], v[118:119], v[126:127], v[150:151] op_sel_hi:[1,0,1]
	v_pk_fma_f32 v[122:123], v[122:123], v[126:127], v[154:155] op_sel_hi:[1,0,1]
	v_pk_fma_f32 v[120:121], v[120:121], v[126:127], v[152:153] op_sel_hi:[1,0,1]
	v_max_f32_e32 v118, 0, v118
	v_pk_fma_f32 v[124:125], v[124:125], v[126:127], v[156:157] op_sel_hi:[1,0,1]
	v_mul_f32_e32 v128, v118, v118
	v_max_f32_e32 v118, 0, v123
	v_max_f32_e32 v119, 0, v119
	v_max_f32_e32 v120, 0, v120
	v_max_f32_e32 v122, 0, v122
	v_mul_f32_e32 v118, v118, v118
	v_mul_f32_e32 v123, v119, v119
	v_max_f32_e32 v119, 0, v124
	v_mul_f32_e32 v124, v120, v120
	v_max_f32_e32 v120, 0, v125
	v_max_f32_e32 v121, 0, v121
	v_pk_fma_f32 v[110:111], v[110:111], v[126:127], v[142:143] op_sel_hi:[1,0,1]
	v_mul_f32_e32 v122, v122, v122
	v_mul_f32_e32 v119, v119, v119
	v_mul_f32_e32 v120, v120, v120
	v_mul_f32_e32 v121, v121, v121
	v_cvt_pk_bf16_f32 v118, v122, v118
	v_pk_fma_f32 v[116:117], v[116:117], v[126:127], v[148:149] op_sel_hi:[1,0,1]
	v_pk_fma_f32 v[114:115], v[114:115], v[126:127], v[146:147] op_sel_hi:[1,0,1]
	v_pk_fma_f32 v[112:113], v[112:113], v[126:127], v[144:145] op_sel_hi:[1,0,1]
	v_max_f32_e32 v110, 0, v110
	v_max_f32_e32 v111, 0, v111
	v_cvt_pk_bf16_f32 v119, v119, v120
	v_cvt_pk_bf16_f32 v120, v128, v123
	v_cvt_pk_bf16_f32 v121, v124, v121
	v_mov_b32_e32 v232, v118
	v_mov_b32_e32 v233, v119
; __device__ __forceinline__ int lane_id() { int l; asm volatile("v_mbcnt_lo_u32_b32 %0, -1, 0\n\tv_mbcnt_hi_u32_b32 %0, -1, %0" : "=v"(l)); return l; }
; __device__ __forceinline__ u32x4 pack8(const f32x4& a, const f32x4& b) { u32x4 w; w.x = cvt_pk_bf16(a[0], a[1]); w.y = cvt_pk_bf16(a[2], a[3]); w.z = cvt_pk_bf16(b[0], b[1]); w.w = cvt_pk_bf16(b[2], b[3]); return w; }
; #define PG8_SH_LDS(sh) do { PG8_LAS const unsigned char* sq_ = slds + RSTAT_OFF + 4096 + (u.ui & 1) * 1024 + (wc * 32 + 8 * fq) * 4; \
;     _Pragma("unroll") for (int bj = 0; bj < 2; ++bj) _Pragma("unroll") for (int n = 0; n < 2; ++n) sh[bj][n] = *(PG8_LAS const f32x4*)(sq_ + (bj * HALF + 4 * n) * 4); } while (0)
; #define PG8_RSTD8_LDS(rsv) do { PG8_LAS const unsigned char* sp_ = slds + RSTAT_OFF + (u.ui & 1) * 2048 + (wr * 64 + fr) * 8; \
;     _Pragma("unroll") for (int ai = 0; ai < 2; ++ai) _Pragma("unroll") for (int m = 0; m < 4; ++m) rsv[ai][m] = *(PG8_LAS const float*)(sp_ + (ai * 128 + m * 16) * 8); } while (0)
;     __device__ __forceinline__ void operator()(const f32x4 (&acc)[2][2][4][2], const Unit& u, int wr, int wc, int fr, int fq) const {
;         { const int l_ = lane_id(); fr = l_ & 15; fq = l_ >> 4; }
;         const int b = u.pm >> 3, c0 = u.pn * BM + wc * 32 + 8 * fq;
;         f32x4 sh[2][2]; PG8_SH_LDS(sh);
;         float rsv[2][4]; PG8_RSTD8_LDS(rsv);
; #pragma unroll
;         for (int ai = 0; ai < 2; ++ai)
; #pragma unroll
;             for (int m = 0; m < 4; ++m) { const int row = PG8_ROW(u, ai, m); const float rs = rsv[ai][m];
; #pragma unroll
;                 for (int bj = 0; bj < 2; ++bj) { f32x4 v0 = acc[ai][bj][m][0] * rs + sh[bj][0], v1 = acc[ai][bj][m][1] * rs + sh[bj][1];
; #pragma unroll
;                     for (int i = 0; i < 4; ++i) { const float a = fmaxf(v0[i], 0.f), c = fmaxf(v1[i], 0.f); v0[i] = a * a; v1[i] = c * c; }
;                     stb(H, (unsigned)((row * DFF + c0 + bj * HALF) * 2), pack8(v0, v1)); } }
;     }
	v_mov_b32_e32 v234, v120
	v_mov_b32_e32 v235, v121
	v_add_u32_e32 v226, v127, v251
	v_max_f32_e32 v112, 0, v112
	v_max_f32_e32 v114, 0, v114
	v_mul_f32_e32 v118, v110, v110
	v_max_f32_e32 v110, 0, v115
	v_mul_f32_e32 v115, v111, v111
	v_max_f32_e32 v111, 0, v116
	v_mul_f32_e32 v110, v110, v110
	v_mul_f32_e32 v111, v111, v111
	v_mul_f32_e32 v116, v112, v112
	v_max_f32_e32 v112, 0, v117
	v_max_f32_e32 v113, 0, v113
	v_mul_f32_e32 v114, v114, v114
	v_mul_f32_e32 v112, v112, v112
	v_mul_f32_e32 v113, v113, v113
	v_add_u32_e32 v117, 0x20100, v174
	v_cvt_pk_bf16_f32 v110, v114, v110
	v_cvt_pk_bf16_f32 v111, v111, v112
	v_pk_fma_f32 v[104:105], v[104:105], v[178:179], v[152:153] op_sel_hi:[1,0,1]
	v_max_f32_e32 v102, 0, v102
	v_cvt_pk_bf16_f32 v112, v118, v115
	v_cvt_pk_bf16_f32 v113, v116, v113
	v_mov_b32_e32 v240, v110
	v_mov_b32_e32 v241, v111
	v_mov_b32_e32 v242, v112
	v_mov_b32_e32 v243, v113
	s_nop 1
	v_mov_b32_dpp v240, v232 row_ror:8 row_mask:0xf bank_mask:0x3
	v_mov_b32_dpp v241, v233 row_ror:8 row_mask:0xf bank_mask:0x3
	v_mov_b32_dpp v242, v234 row_ror:8 row_mask:0xf bank_mask:0x3
	v_mov_b32_dpp v243, v235 row_ror:8 row_mask:0xf bank_mask:0x3
	v_mov_b32_dpp v232, v110 row_ror:8 row_mask:0xf bank_mask:0xc
	v_mov_b32_dpp v233, v111 row_ror:8 row_mask:0xf bank_mask:0xc
	v_mov_b32_dpp v234, v112 row_ror:8 row_mask:0xf bank_mask:0xc
	v_mov_b32_dpp v235, v113 row_ror:8 row_mask:0xf bank_mask:0xc
	global_store_dwordx4 v226, v[232:235], s[14:15]
	v_add_u32_e32 v248, 0x10000, v226
	global_store_dwordx4 v248, v[240:243], s[14:15]
	v_pk_fma_f32 v[108:109], v[108:109], v[178:179], v[156:157] op_sel_hi:[1,0,1]
	v_max_f32_e32 v103, 0, v103
	v_mul_f32_e32 v111, v102, v102
	v_max_f32_e32 v102, 0, v107
	v_max_f32_e32 v104, 0, v104
	v_max_f32_e32 v106, 0, v106
	v_mul_f32_e32 v102, v102, v102
	v_mul_f32_e32 v107, v103, v103
	v_max_f32_e32 v103, 0, v108
	v_mul_f32_e32 v108, v104, v104
	v_max_f32_e32 v104, 0, v109
	v_max_f32_e32 v105, 0, v105
	v_pk_fma_f32 v[94:95], v[94:95], v[178:179], v[142:143] op_sel_hi:[1,0,1]
	v_add_u32_e32 v110, 0x40000, v174
	v_mul_f32_e32 v106, v106, v106
	v_mul_f32_e32 v103, v103, v103
	v_mul_f32_e32 v104, v104, v104
	v_mul_f32_e32 v105, v105, v105
	v_cvt_pk_bf16_f32 v102, v106, v102
	v_pk_fma_f32 v[100:101], v[100:101], v[178:179], v[148:149] op_sel_hi:[1,0,1]
	v_pk_fma_f32 v[98:99], v[98:99], v[178:179], v[146:147] op_sel_hi:[1,0,1]
	v_pk_fma_f32 v[96:97], v[96:97], v[178:179], v[144:145] op_sel_hi:[1,0,1]
	v_max_f32_e32 v94, 0, v94
	v_max_f32_e32 v95, 0, v95
	v_cvt_pk_bf16_f32 v103, v103, v104
	v_cvt_pk_bf16_f32 v104, v111, v107
	v_cvt_pk_bf16_f32 v105, v108, v105
	v_mov_b32_e32 v232, v102
	v_mov_b32_e32 v233, v103
	v_mov_b32_e32 v234, v104
	v_mov_b32_e32 v235, v105
	v_add_u32_e32 v226, v110, v251
	v_max_f32_e32 v96, 0, v96
	v_max_f32_e32 v98, 0, v98
	v_mul_f32_e32 v102, v94, v94
	v_max_f32_e32 v94, 0, v99
	v_mul_f32_e32 v99, v95, v95
	v_max_f32_e32 v95, 0, v100
	v_mul_f32_e32 v94, v94, v94
	v_mul_f32_e32 v95, v95, v95
	v_mul_f32_e32 v100, v96, v96
	v_max_f32_e32 v96, 0, v101
	v_max_f32_e32 v97, 0, v97
	v_mul_f32_e32 v98, v98, v98
	v_mul_f32_e32 v96, v96, v96
	v_mul_f32_e32 v97, v97, v97
	v_add_u32_e32 v101, 0x40100, v174
	v_cvt_pk_bf16_f32 v94, v98, v94
	v_cvt_pk_bf16_f32 v95, v95, v96
	v_cvt_pk_bf16_f32 v96, v102, v99
	v_cvt_pk_bf16_f32 v97, v100, v97
	v_mov_b32_e32 v240, v94
	v_mov_b32_e32 v241, v95
	v_mov_b32_e32 v242, v96
	v_mov_b32_e32 v243, v97
	s_nop 1
	v_mov_b32_dpp v240, v232 row_ror:8 row_mask:0xf bank_mask:0x3
	v_mov_b32_dpp v241, v233 row_ror:8 row_mask:0xf bank_mask:0x3
	v_mov_b32_dpp v242, v234 row_ror:8 row_mask:0xf bank_mask:0x3
	v_mov_b32_dpp v243, v235 row_ror:8 row_mask:0xf bank_mask:0x3
	v_mov_b32_dpp v232, v94 row_ror:8 row_mask:0xf bank_mask:0xc
	v_mov_b32_dpp v233, v95 row_ror:8 row_mask:0xf bank_mask:0xc
	v_mov_b32_dpp v234, v96 row_ror:8 row_mask:0xf bank_mask:0xc
	v_mov_b32_dpp v235, v97 row_ror:8 row_mask:0xf bank_mask:0xc
	global_store_dwordx4 v226, v[232:235], s[14:15]
	v_add_u32_e32 v248, 0x10000, v226
	global_store_dwordx4 v248, v[240:243], s[14:15]
	s_waitcnt lgkmcnt(0)
	v_pk_fma_f32 v[70:71], v[70:71], v[166:167], v[150:151] op_sel_hi:[1,0,1]
	v_pk_fma_f32 v[74:75], v[74:75], v[166:167], v[154:155] op_sel_hi:[1,0,1]
	v_add_u32_e32 v95, 0x60000, v174
	v_mov_b32_e32 v94, v179
	v_pk_fma_f32 v[86:87], v[86:87], v[94:95], v[150:151] op_sel_hi:[1,0,1]
	v_pk_fma_f32 v[90:91], v[90:91], v[94:95], v[154:155] op_sel_hi:[1,0,1]
	v_pk_fma_f32 v[88:89], v[88:89], v[94:95], v[152:153] op_sel_hi:[1,0,1]
	v_max_f32_e32 v86, 0, v86
	v_pk_fma_f32 v[92:93], v[92:93], v[94:95], v[156:157] op_sel_hi:[1,0,1]
	v_mul_f32_e32 v96, v86, v86
	v_max_f32_e32 v86, 0, v91
	v_max_f32_e32 v87, 0, v87
	v_max_f32_e32 v88, 0, v88
	v_max_f32_e32 v90, 0, v90
	v_mul_f32_e32 v86, v86, v86
	v_mul_f32_e32 v91, v87, v87
	v_max_f32_e32 v87, 0, v92
	v_mul_f32_e32 v92, v88, v88
	v_max_f32_e32 v88, 0, v93
	v_max_f32_e32 v89, 0, v89
	v_pk_fma_f32 v[78:79], v[78:79], v[94:95], v[142:143] op_sel_hi:[1,0,1]
	v_mul_f32_e32 v90, v90, v90
	v_mul_f32_e32 v87, v87, v87
	v_mul_f32_e32 v88, v88, v88
	v_mul_f32_e32 v89, v89, v89
	v_cvt_pk_bf16_f32 v86, v90, v86
	v_pk_fma_f32 v[84:85], v[84:85], v[94:95], v[148:149] op_sel_hi:[1,0,1]
	v_pk_fma_f32 v[82:83], v[82:83], v[94:95], v[146:147] op_sel_hi:[1,0,1]
	v_pk_fma_f32 v[80:81], v[80:81], v[94:95], v[144:145] op_sel_hi:[1,0,1]
	v_max_f32_e32 v78, 0, v78
	v_max_f32_e32 v79, 0, v79
	v_cvt_pk_bf16_f32 v87, v87, v88
	v_cvt_pk_bf16_f32 v88, v96, v91
	v_cvt_pk_bf16_f32 v89, v92, v89
	v_mov_b32_e32 v232, v86
	v_mov_b32_e32 v233, v87
	v_mov_b32_e32 v234, v88
	v_mov_b32_e32 v235, v89
	v_add_u32_e32 v226, v95, v251
; __device__ __forceinline__ u32x4 pack8(const f32x4& a, const f32x4& b) { u32x4 w; w.x = cvt_pk_bf16(a[0], a[1]); w.y = cvt_pk_bf16(a[2], a[3]); w.z = cvt_pk_bf16(b[0], b[1]); w.w = cvt_pk_bf16(b[2], b[3]); return w; }
;     __device__ __forceinline__ void operator()(const f32x4 (&acc)[2][2][4][2], const Unit& u, int wr, int wc, int fr, int fq) const {
;     ...
; #pragma unroll
;         for (int ai = 0; ai < 2; ++ai)
; #pragma unroll
;             for (int m = 0; m < 4; ++m) { const int row = PG8_ROW(u, ai, m); const float rs = rsv[ai][m];
; #pragma unroll
;                 for (int bj = 0; bj < 2; ++bj) { f32x4 v0 = acc[ai][bj][m][0] * rs + sh[bj][0], v1 = acc[ai][bj][m][1] * rs + sh[bj][1];
; #pragma unroll
;                     for (int i = 0; i < 4; ++i) { const float a = fmaxf(v0[i], 0.f), c = fmaxf(v1[i], 0.f); v0[i] = a * a; v1[i] = c * c; }
;                     stb(H, (unsigned)((row * DFF + c0 + bj * HALF) * 2), pack8(v0, v1)); } }
	v_max_f32_e32 v80, 0, v80
	v_max_f32_e32 v82, 0, v82
	v_mul_f32_e32 v86, v78, v78
	v_max_f32_e32 v78, 0, v83
	v_mul_f32_e32 v83, v79, v79
	v_max_f32_e32 v79, 0, v84
	v_mul_f32_e32 v78, v78, v78
	v_mul_f32_e32 v79, v79, v79
	v_mul_f32_e32 v84, v80, v80
	v_max_f32_e32 v80, 0, v85
	v_max_f32_e32 v81, 0, v81
	v_mul_f32_e32 v82, v82, v82
	v_mul_f32_e32 v80, v80, v80
	v_mul_f32_e32 v81, v81, v81
	v_add_u32_e32 v85, 0x60100, v174
	v_cvt_pk_bf16_f32 v78, v82, v78
	v_cvt_pk_bf16_f32 v79, v79, v80
	v_pk_fma_f32 v[72:73], v[72:73], v[166:167], v[152:153] op_sel_hi:[1,0,1]
	v_max_f32_e32 v70, 0, v70
	v_cvt_pk_bf16_f32 v80, v86, v83
	v_cvt_pk_bf16_f32 v81, v84, v81
	v_mov_b32_e32 v240, v78
	v_mov_b32_e32 v241, v79
	v_mov_b32_e32 v242, v80
	v_mov_b32_e32 v243, v81
	s_nop 1
	v_mov_b32_dpp v240, v232 row_ror:8 row_mask:0xf bank_mask:0x3
	v_mov_b32_dpp v241, v233 row_ror:8 row_mask:0xf bank_mask:0x3
	v_mov_b32_dpp v242, v234 row_ror:8 row_mask:0xf bank_mask:0x3
	v_mov_b32_dpp v243, v235 row_ror:8 row_mask:0xf bank_mask:0x3
	v_mov_b32_dpp v232, v78 row_ror:8 row_mask:0xf bank_mask:0xc
	v_mov_b32_dpp v233, v79 row_ror:8 row_mask:0xf bank_mask:0xc
	v_mov_b32_dpp v234, v80 row_ror:8 row_mask:0xf bank_mask:0xc
	v_mov_b32_dpp v235, v81 row_ror:8 row_mask:0xf bank_mask:0xc
	global_store_dwordx4 v226, v[232:235], s[14:15]
	v_add_u32_e32 v248, 0x10000, v226
	global_store_dwordx4 v248, v[240:243], s[14:15]
	v_pk_fma_f32 v[76:77], v[76:77], v[166:167], v[156:157] op_sel_hi:[1,0,1]
	v_max_f32_e32 v71, 0, v71
	v_mul_f32_e32 v79, v70, v70
	v_max_f32_e32 v70, 0, v75
	v_max_f32_e32 v72, 0, v72
	v_max_f32_e32 v74, 0, v74
	v_mul_f32_e32 v70, v70, v70
	v_mul_f32_e32 v75, v71, v71
	v_max_f32_e32 v71, 0, v76
	v_mul_f32_e32 v76, v72, v72
	v_max_f32_e32 v72, 0, v77
	v_max_f32_e32 v73, 0, v73
	v_pk_fma_f32 v[62:63], v[62:63], v[166:167], v[142:143] op_sel_hi:[1,0,1]
	v_add_u32_e32 v78, 0x100000, v174
	v_mul_f32_e32 v74, v74, v74
	v_mul_f32_e32 v71, v71, v71
	v_mul_f32_e32 v72, v72, v72
	v_mul_f32_e32 v73, v73, v73
	v_cvt_pk_bf16_f32 v70, v74, v70
	v_pk_fma_f32 v[68:69], v[68:69], v[166:167], v[148:149] op_sel_hi:[1,0,1]
	v_pk_fma_f32 v[66:67], v[66:67], v[166:167], v[146:147] op_sel_hi:[1,0,1]
	v_pk_fma_f32 v[64:65], v[64:65], v[166:167], v[144:145] op_sel_hi:[1,0,1]
	v_max_f32_e32 v62, 0, v62
	v_max_f32_e32 v63, 0, v63
	v_cvt_pk_bf16_f32 v71, v71, v72
	v_cvt_pk_bf16_f32 v72, v79, v75
	v_cvt_pk_bf16_f32 v73, v76, v73
	v_mov_b32_e32 v232, v70
	v_mov_b32_e32 v233, v71
	v_mov_b32_e32 v234, v72
	v_mov_b32_e32 v235, v73
	v_add_u32_e32 v226, v78, v251
	v_max_f32_e32 v64, 0, v64
	v_max_f32_e32 v66, 0, v66
	v_mul_f32_e32 v70, v62, v62
	v_max_f32_e32 v62, 0, v67
	v_mul_f32_e32 v67, v63, v63
	v_max_f32_e32 v63, 0, v68
	v_mul_f32_e32 v62, v62, v62
	v_mul_f32_e32 v63, v63, v63
	v_mul_f32_e32 v68, v64, v64
	v_max_f32_e32 v64, 0, v69
	v_max_f32_e32 v65, 0, v65
	v_mul_f32_e32 v66, v66, v66
	v_mul_f32_e32 v64, v64, v64
	v_mul_f32_e32 v65, v65, v65
	v_add_u32_e32 v69, 0x100100, v174
	v_cvt_pk_bf16_f32 v62, v66, v62
	v_cvt_pk_bf16_f32 v63, v63, v64
	v_cvt_pk_bf16_f32 v64, v70, v67
	v_cvt_pk_bf16_f32 v65, v68, v65
	v_mov_b32_e32 v240, v62
	v_mov_b32_e32 v241, v63
	v_mov_b32_e32 v242, v64
	v_mov_b32_e32 v243, v65
	s_nop 1
	v_mov_b32_dpp v240, v232 row_ror:8 row_mask:0xf bank_mask:0x3
	v_mov_b32_dpp v241, v233 row_ror:8 row_mask:0xf bank_mask:0x3
	v_mov_b32_dpp v242, v234 row_ror:8 row_mask:0xf bank_mask:0x3
	v_mov_b32_dpp v243, v235 row_ror:8 row_mask:0xf bank_mask:0x3
	v_mov_b32_dpp v232, v62 row_ror:8 row_mask:0xf bank_mask:0xc
	v_mov_b32_dpp v233, v63 row_ror:8 row_mask:0xf bank_mask:0xc
	v_mov_b32_dpp v234, v64 row_ror:8 row_mask:0xf bank_mask:0xc
	v_mov_b32_dpp v235, v65 row_ror:8 row_mask:0xf bank_mask:0xc
	global_store_dwordx4 v226, v[232:235], s[14:15]
	v_add_u32_e32 v248, 0x10000, v226
	global_store_dwordx4 v248, v[240:243], s[14:15]
	v_pk_fma_f32 v[38:39], v[38:39], v[164:165], v[150:151] op_sel_hi:[1,0,1]
	v_pk_fma_f32 v[42:43], v[42:43], v[164:165], v[154:155] op_sel_hi:[1,0,1]
	v_add_u32_e32 v63, 0x120000, v174
	v_mov_b32_e32 v62, v167
	v_pk_fma_f32 v[54:55], v[54:55], v[62:63], v[150:151] op_sel_hi:[1,0,1]
	v_pk_fma_f32 v[58:59], v[58:59], v[62:63], v[154:155] op_sel_hi:[1,0,1]
	v_pk_fma_f32 v[56:57], v[56:57], v[62:63], v[152:153] op_sel_hi:[1,0,1]
	v_max_f32_e32 v54, 0, v54
	v_pk_fma_f32 v[60:61], v[60:61], v[62:63], v[156:157] op_sel_hi:[1,0,1]
	v_mul_f32_e32 v64, v54, v54
	v_max_f32_e32 v54, 0, v59
	v_max_f32_e32 v55, 0, v55
	v_max_f32_e32 v56, 0, v56
	v_max_f32_e32 v58, 0, v58
	v_mul_f32_e32 v54, v54, v54
	v_mul_f32_e32 v59, v55, v55
	v_max_f32_e32 v55, 0, v60
	v_mul_f32_e32 v60, v56, v56
	v_max_f32_e32 v56, 0, v61
	v_max_f32_e32 v57, 0, v57
	v_pk_fma_f32 v[46:47], v[46:47], v[62:63], v[142:143] op_sel_hi:[1,0,1]
	v_mul_f32_e32 v58, v58, v58
	v_mul_f32_e32 v55, v55, v55
	v_mul_f32_e32 v56, v56, v56
	v_mul_f32_e32 v57, v57, v57
	v_cvt_pk_bf16_f32 v54, v58, v54
	v_pk_fma_f32 v[52:53], v[52:53], v[62:63], v[148:149] op_sel_hi:[1,0,1]
	v_pk_fma_f32 v[50:51], v[50:51], v[62:63], v[146:147] op_sel_hi:[1,0,1]
	v_pk_fma_f32 v[48:49], v[48:49], v[62:63], v[144:145] op_sel_hi:[1,0,1]
	v_max_f32_e32 v46, 0, v46
	v_max_f32_e32 v47, 0, v47
	v_cvt_pk_bf16_f32 v55, v55, v56
	v_cvt_pk_bf16_f32 v56, v64, v59
	v_cvt_pk_bf16_f32 v57, v60, v57
	v_mov_b32_e32 v232, v54
	v_mov_b32_e32 v233, v55
	v_mov_b32_e32 v234, v56
	v_mov_b32_e32 v235, v57
	v_add_u32_e32 v226, v63, v251
	v_max_f32_e32 v48, 0, v48
	v_max_f32_e32 v50, 0, v50
	v_mul_f32_e32 v54, v46, v46
	v_max_f32_e32 v46, 0, v51
	v_mul_f32_e32 v51, v47, v47
	v_max_f32_e32 v47, 0, v52
	v_mul_f32_e32 v46, v46, v46
	v_mul_f32_e32 v47, v47, v47
; __device__ __forceinline__ u32x4 pack8(const f32x4& a, const f32x4& b) { u32x4 w; w.x = cvt_pk_bf16(a[0], a[1]); w.y = cvt_pk_bf16(a[2], a[3]); w.z = cvt_pk_bf16(b[0], b[1]); w.w = cvt_pk_bf16(b[2], b[3]); return w; }
;     __device__ __forceinline__ void operator()(const f32x4 (&acc)[2][2][4][2], const Unit& u, int wr, int wc, int fr, int fq) const {
;     ...
; #pragma unroll
;         for (int ai = 0; ai < 2; ++ai)
; #pragma unroll
;             for (int m = 0; m < 4; ++m) { const int row = PG8_ROW(u, ai, m); const float rs = rsv[ai][m];
; #pragma unroll
;                 for (int bj = 0; bj < 2; ++bj) { f32x4 v0 = acc[ai][bj][m][0] * rs + sh[bj][0], v1 = acc[ai][bj][m][1] * rs + sh[bj][1];
; #pragma unroll
;                     for (int i = 0; i < 4; ++i) { const float a = fmaxf(v0[i], 0.f), c = fmaxf(v1[i], 0.f); v0[i] = a * a; v1[i] = c * c; }
;                     stb(H, (unsigned)((row * DFF + c0 + bj * HALF) * 2), pack8(v0, v1)); } }
	v_mul_f32_e32 v52, v48, v48
	v_max_f32_e32 v48, 0, v53
	v_max_f32_e32 v49, 0, v49
	v_mul_f32_e32 v50, v50, v50
	v_mul_f32_e32 v48, v48, v48
	v_mul_f32_e32 v49, v49, v49
	v_add_u32_e32 v53, 0x120100, v174
	v_cvt_pk_bf16_f32 v46, v50, v46
	v_cvt_pk_bf16_f32 v47, v47, v48
	v_pk_fma_f32 v[40:41], v[40:41], v[164:165], v[152:153] op_sel_hi:[1,0,1]
	v_max_f32_e32 v38, 0, v38
	v_cvt_pk_bf16_f32 v48, v54, v51
	v_cvt_pk_bf16_f32 v49, v52, v49
	v_mov_b32_e32 v240, v46
	v_mov_b32_e32 v241, v47
	v_mov_b32_e32 v242, v48
	v_mov_b32_e32 v243, v49
	s_nop 1
	v_mov_b32_dpp v240, v232 row_ror:8 row_mask:0xf bank_mask:0x3
	v_mov_b32_dpp v241, v233 row_ror:8 row_mask:0xf bank_mask:0x3
	v_mov_b32_dpp v242, v234 row_ror:8 row_mask:0xf bank_mask:0x3
	v_mov_b32_dpp v243, v235 row_ror:8 row_mask:0xf bank_mask:0x3
	v_mov_b32_dpp v232, v46 row_ror:8 row_mask:0xf bank_mask:0xc
	v_mov_b32_dpp v233, v47 row_ror:8 row_mask:0xf bank_mask:0xc
	v_mov_b32_dpp v234, v48 row_ror:8 row_mask:0xf bank_mask:0xc
	v_mov_b32_dpp v235, v49 row_ror:8 row_mask:0xf bank_mask:0xc
	global_store_dwordx4 v226, v[232:235], s[14:15]
	v_add_u32_e32 v248, 0x10000, v226
	global_store_dwordx4 v248, v[240:243], s[14:15]
	v_pk_fma_f32 v[44:45], v[44:45], v[164:165], v[156:157] op_sel_hi:[1,0,1]
	v_max_f32_e32 v39, 0, v39
	v_mul_f32_e32 v47, v38, v38
	v_max_f32_e32 v38, 0, v43
	v_max_f32_e32 v40, 0, v40
	v_max_f32_e32 v42, 0, v42
	v_mul_f32_e32 v38, v38, v38
	v_mul_f32_e32 v43, v39, v39
	v_max_f32_e32 v39, 0, v44
	v_mul_f32_e32 v44, v40, v40
	v_max_f32_e32 v40, 0, v45
	v_max_f32_e32 v41, 0, v41
	v_pk_fma_f32 v[30:31], v[30:31], v[164:165], v[142:143] op_sel_hi:[1,0,1]
	v_add_u32_e32 v46, 0x140000, v174
	v_mul_f32_e32 v42, v42, v42
	v_mul_f32_e32 v39, v39, v39
	v_mul_f32_e32 v40, v40, v40
	v_mul_f32_e32 v41, v41, v41
	v_cvt_pk_bf16_f32 v38, v42, v38
	v_pk_fma_f32 v[36:37], v[36:37], v[164:165], v[148:149] op_sel_hi:[1,0,1]
	v_pk_fma_f32 v[34:35], v[34:35], v[164:165], v[146:147] op_sel_hi:[1,0,1]
	v_pk_fma_f32 v[32:33], v[32:33], v[164:165], v[144:145] op_sel_hi:[1,0,1]
	v_max_f32_e32 v30, 0, v30
	v_max_f32_e32 v31, 0, v31
	v_cvt_pk_bf16_f32 v39, v39, v40
	v_cvt_pk_bf16_f32 v40, v47, v43
	v_cvt_pk_bf16_f32 v41, v44, v41
	v_mov_b32_e32 v232, v38
	v_mov_b32_e32 v233, v39
	v_mov_b32_e32 v234, v40
	v_mov_b32_e32 v235, v41
	v_add_u32_e32 v226, v46, v251
	v_max_f32_e32 v32, 0, v32
	v_max_f32_e32 v34, 0, v34
	v_mul_f32_e32 v38, v30, v30
	v_max_f32_e32 v30, 0, v35
	v_mul_f32_e32 v35, v31, v31
	v_max_f32_e32 v31, 0, v36
	v_mul_f32_e32 v30, v30, v30
	v_mul_f32_e32 v31, v31, v31
	v_mul_f32_e32 v36, v32, v32
	v_max_f32_e32 v32, 0, v37
	v_max_f32_e32 v33, 0, v33
	v_mul_f32_e32 v34, v34, v34
	v_mul_f32_e32 v32, v32, v32
	v_mul_f32_e32 v33, v33, v33
	v_add_u32_e32 v37, 0x140100, v174
	v_cvt_pk_bf16_f32 v30, v34, v30
	v_cvt_pk_bf16_f32 v31, v31, v32
	v_cvt_pk_bf16_f32 v32, v38, v35
	v_cvt_pk_bf16_f32 v33, v36, v33
	v_mov_b32_e32 v240, v30
	v_mov_b32_e32 v241, v31
	v_mov_b32_e32 v242, v32
	v_mov_b32_e32 v243, v33
	s_nop 1
	v_mov_b32_dpp v240, v232 row_ror:8 row_mask:0xf bank_mask:0x3
	v_mov_b32_dpp v241, v233 row_ror:8 row_mask:0xf bank_mask:0x3
	v_mov_b32_dpp v242, v234 row_ror:8 row_mask:0xf bank_mask:0x3
	v_mov_b32_dpp v243, v235 row_ror:8 row_mask:0xf bank_mask:0x3
	v_mov_b32_dpp v232, v30 row_ror:8 row_mask:0xf bank_mask:0xc
	v_mov_b32_dpp v233, v31 row_ror:8 row_mask:0xf bank_mask:0xc
	v_mov_b32_dpp v234, v32 row_ror:8 row_mask:0xf bank_mask:0xc
	v_mov_b32_dpp v235, v33 row_ror:8 row_mask:0xf bank_mask:0xc
	global_store_dwordx4 v226, v[232:235], s[14:15]
	v_add_u32_e32 v248, 0x10000, v226
	global_store_dwordx4 v248, v[240:243], s[14:15]
	s_and_b64 vcc, exec, s[8:9]
	s_mov_b64 s[8:9], -1
	v_add_u32_e32 v31, 0x160000, v174
	v_mov_b32_e32 v30, v165
	v_pk_fma_f32 v[22:23], v[22:23], v[30:31], v[150:151] op_sel_hi:[1,0,1]
	v_pk_fma_f32 v[26:27], v[26:27], v[30:31], v[154:155] op_sel_hi:[1,0,1]
	v_pk_fma_f32 v[24:25], v[24:25], v[30:31], v[152:153] op_sel_hi:[1,0,1]
	v_max_f32_e32 v22, 0, v22
	v_pk_fma_f32 v[28:29], v[28:29], v[30:31], v[156:157] op_sel_hi:[1,0,1]
	v_mul_f32_e32 v32, v22, v22
	v_max_f32_e32 v22, 0, v27
	v_max_f32_e32 v23, 0, v23
	v_max_f32_e32 v24, 0, v24
	v_max_f32_e32 v26, 0, v26
	v_mul_f32_e32 v22, v22, v22
	v_mul_f32_e32 v27, v23, v23
	v_max_f32_e32 v23, 0, v28
	v_mul_f32_e32 v28, v24, v24
	v_max_f32_e32 v24, 0, v29
	v_max_f32_e32 v25, 0, v25
	v_pk_fma_f32 v[16:17], v[16:17], v[30:31], v[144:145] op_sel_hi:[1,0,1]
	v_pk_fma_f32 v[14:15], v[14:15], v[30:31], v[142:143] op_sel_hi:[1,0,1]
	v_mul_f32_e32 v26, v26, v26
	v_mul_f32_e32 v23, v23, v23
	v_mul_f32_e32 v24, v24, v24
	v_mul_f32_e32 v25, v25, v25
	v_cvt_pk_bf16_f32 v22, v26, v22
	v_pk_fma_f32 v[20:21], v[20:21], v[30:31], v[148:149] op_sel_hi:[1,0,1]
	v_pk_fma_f32 v[18:19], v[18:19], v[30:31], v[146:147] op_sel_hi:[1,0,1]
	v_max_f32_e32 v14, 0, v14
	v_max_f32_e32 v15, 0, v15
	v_max_f32_e32 v16, 0, v16
	v_cvt_pk_bf16_f32 v23, v23, v24
	v_cvt_pk_bf16_f32 v24, v32, v27
	v_cvt_pk_bf16_f32 v25, v28, v25
	v_mov_b32_e32 v232, v22
	v_mov_b32_e32 v233, v23
	v_mov_b32_e32 v234, v24
	v_mov_b32_e32 v235, v25
	v_add_u32_e32 v226, v31, v251
	v_max_f32_e32 v17, 0, v17
	v_max_f32_e32 v18, 0, v18
	v_mul_f32_e32 v22, v14, v14
	v_max_f32_e32 v14, 0, v19
	v_mul_f32_e32 v19, v15, v15
	v_max_f32_e32 v15, 0, v20
	v_mul_f32_e32 v20, v16, v16
	v_max_f32_e32 v16, 0, v21
	v_mul_f32_e32 v14, v14, v14
	v_mul_f32_e32 v15, v15, v15
	v_mul_f32_e32 v16, v16, v16
	v_mul_f32_e32 v17, v17, v17
	v_add_u32_e32 v21, 0x160100, v174
	v_mul_f32_e32 v18, v18, v18
	v_cvt_pk_bf16_f32 v14, v18, v14
	v_cvt_pk_bf16_f32 v15, v15, v16
	v_cvt_pk_bf16_f32 v16, v22, v19
	v_cvt_pk_bf16_f32 v17, v20, v17
	v_mov_b32_e32 v240, v14
	v_mov_b32_e32 v241, v15
	v_mov_b32_e32 v242, v16
	v_mov_b32_e32 v243, v17
	s_nop 1
	v_mov_b32_dpp v240, v232 row_ror:8 row_mask:0xf bank_mask:0x3
	v_mov_b32_dpp v241, v233 row_ror:8 row_mask:0xf bank_mask:0x3
	v_mov_b32_dpp v242, v234 row_ror:8 row_mask:0xf bank_mask:0x3
	v_mov_b32_dpp v243, v235 row_ror:8 row_mask:0xf bank_mask:0x3
	v_mov_b32_dpp v232, v14 row_ror:8 row_mask:0xf bank_mask:0xc
	v_mov_b32_dpp v233, v15 row_ror:8 row_mask:0xf bank_mask:0xc
	v_mov_b32_dpp v234, v16 row_ror:8 row_mask:0xf bank_mask:0xc
	v_mov_b32_dpp v235, v17 row_ror:8 row_mask:0xf bank_mask:0xc
	global_store_dwordx4 v226, v[232:235], s[14:15]
	v_add_u32_e32 v248, 0x10000, v226
	global_store_dwordx4 v248, v[240:243], s[14:15]
	s_cbranch_vccnz .LBB13_1066
	s_andn2_b64 vcc, exec, s[12:13]
	s_cbranch_vccnz .LBB13_1065
	s_barrier
	s_branch .LBB13_1065

; #define PG8_STAGE(bufoff, gbase, voff) do { const char* gb_ = (const char*)(gbase); asm volatile("" : "+s"(gb_));     \
;         _Pragma("unroll") for (int _i = 0; _i < 2; ++_i) \
;         __builtin_amdgcn_global_load_lds((const unsigned*)(gb_ + (voff)[_i]), (PG8_LAS unsigned*)(lds + (bufoff) + ldsw + _i * 8192), 16, 0, 0); } while (0)
; template <class Epi, class Sched, bool ALIGN_EPI = false, bool SP2 = false>
; __device__ __forceinline__ void gemm_phase(PG8_LAS unsigned char* lds, const Gemm g, const Sched& S, const Epi& E, int wid0) {
;     ...
;     for (int i = 0; i < 2; ++i) { int R, C; stage_rc(tid * 16 + i * 8192, R, C); const int Rb = Epi::PERM ? ((R & ~31) + perm32(R & 31)) : R;
;         voffA[i] = (unsigned)(R * LDA + C) * 2u; voffB[i] = (unsigned)(Rb * K + C) * 2u; }
;     ...
;     if constexpr (SP2) {
;         PG8_STAGE(PG8_SB(0, 0), cB, voffB); PG8_STAGE(PG8_SB(0, 1), cB + hstep, voffB); PG8_STAGE(PG8_SA(0, 0), cA, voffA); PG8_STAGE(PG8_SA(0, 1), cA + hstepA, voffA);
.LBB13_2040:
	s_or_b64 exec, exec, s[8:9]
	v_ashrrev_i32_e32 v8, 31, v169
	v_lshrrev_b32_e32 v8, 22, v8
	v_add_u32_e32 v8, v169, v8
	v_ashrrev_i32_e32 v8, 10, v8
	v_mul_i32_i24_e32 v15, 0x400, v8
	v_sub_u32_e32 v15, v169, v15
	s_lshl_b64 s[6:7], s[6:7], 15
	v_lshrrev_b32_e32 v16, 4, v15
	s_add_u32 s33, s18, 0x4000000
	v_bitop3_b32 v15, v16, v15, 32 bitop3:0x6c
	s_addc_u32 s42, s19, 0
	v_ashrrev_i32_e32 v17, 31, v15
	s_add_u32 s43, s18, 0x2d00000
	v_lshrrev_b32_e32 v17, 26, v17
	s_addc_u32 s44, s19, 0
	s_ashr_i32 s27, s26, 31
	v_add_u32_e32 v17, v15, v17
	s_lshl_b64 s[8:9], s[26:27], 19
	v_ashrrev_i32_e32 v18, 6, v17
	v_and_b32_e32 v17, 0xc0, v17
	s_add_u32 s8, s33, s8
	v_sub_u32_e32 v15, v15, v17
	v_mov_b32_e32 v17, 1
	s_addc_u32 s9, s42, s9
	s_ashr_i32 s29, s28, 31
	v_lshlrev_b32_e32 v16, 3, v8
	v_lshlrev_b32_e32 v8, 5, v8
	v_ashrrev_i16_sdwa v15, v17, sext(v15) dst_sel:DWORD dst_unused:UNUSED_PAD src0_sel:DWORD src1_sel:BYTE_0
	s_lshl_b64 s[12:13], s[28:29], 19
	v_and_b32_e32 v16, -16, v16
	v_and_b32_e32 v8, 32, v8
	v_bfe_i32 v15, v15, 0, 16
	s_add_u32 s34, s43, s12
	v_add_u32_e32 v16, v18, v16
	v_and_b32_e32 v18, 3, v18
	s_mov_b32 s12, 0x1fffe0
	v_add_lshl_u32 v8, v8, v15, 1
	v_add_u32_e32 v15, 0x2000, v169
	v_lshlrev_b32_e32 v19, 1, v16
	v_lshrrev_b32_e32 v20, 2, v16
	v_and_or_b32 v18, v16, s12, v18
	v_lshl_add_u32 v158, v16, 11, v8
	v_ashrrev_i32_e32 v16, 31, v15
	v_lshrrev_b32_e32 v16, 22, v16
	v_and_b32_e32 v19, 24, v19
	v_and_b32_e32 v20, 4, v20
	v_add_u32_e32 v16, v15, v16
	v_or3_b32 v18, v18, v20, v19
	v_ashrrev_i32_e32 v16, 10, v16
	v_lshrrev_b32_e32 v250, 5, v18
	v_and_b32_e32 v251, 31, v18
	v_lshl_add_u32 v251, v250, 6, v251
	v_lshl_add_u32 v8, v251, 11, v8
	v_mul_i32_i24_e32 v18, 0x400, v16
	v_sub_u32_e32 v15, v15, v18
	v_lshrrev_b32_e32 v18, 4, v15
	v_bitop3_b32 v15, v18, v15, 32 bitop3:0x6c
	v_ashrrev_i32_e32 v19, 31, v15
	v_lshrrev_b32_e32 v19, 26, v19
	v_lshlrev_b32_e32 v18, 3, v16
	v_add_u32_e32 v19, v15, v19
	v_and_b32_e32 v18, -16, v18
	v_ashrrev_i32_e32 v20, 6, v19
	v_and_b32_e32 v19, 0xc0, v19
	s_addc_u32 s35, s44, s13
	v_add_u32_e32 v18, v20, v18
	v_sub_u32_e32 v15, v15, v19
	s_ashr_i32 s20, s17, 6
	v_lshlrev_b32_e32 v16, 5, v16
	v_ashrrev_i16_sdwa v15, v17, sext(v15) dst_sel:DWORD dst_unused:UNUSED_PAD src0_sel:DWORD src1_sel:BYTE_0
	v_lshlrev_b32_e32 v17, 1, v18
	v_lshrrev_b32_e32 v19, 2, v18
	v_and_b32_e32 v20, 3, v20
	s_lshl_b32 s27, s20, 10
	v_and_b32_e32 v16, 32, v16
	v_bfe_i32 v15, v15, 0, 16
	v_and_b32_e32 v17, 24, v17
	v_and_b32_e32 v19, 4, v19
	v_and_or_b32 v20, v18, s12, v20
	s_add_i32 s29, s27, 0
	v_or3_b32 v17, v20, v19, v17
	v_add_lshl_u32 v15, v16, v15, 1
	s_mov_b64 s[12:13], s[34:35]
	s_add_i32 m0, s29, 0x10000
	s_ashr_i32 s6, s17, 8
	v_lshrrev_b32_e32 v250, 5, v17
	v_and_b32_e32 v251, 31, v17
	v_lshl_add_u32 v251, v250, 6, v251
	v_lshl_add_u32 v162, v251, 11, v15
	v_lshl_add_u32 v160, v18, 11, v15
	global_load_lds_dwordx4 v8, s[12:13]
	s_add_i32 m0, s29, 0x12000
	v_mov_b32_e32 v163, v9
	global_load_lds_dwordx4 v162, s[12:13]
	s_add_u32 s12, s34, 0x10000
	s_addc_u32 s13, s35, 0
	s_add_i32 m0, s29, 0x14000
	s_add_i32 s45, s29, 0x2000
	global_load_lds_dwordx4 v8, s[12:13]
	s_add_i32 m0, s29, 0x16000
	v_mov_b32_e32 v159, v9
	global_load_lds_dwordx4 v162, s[12:13]
	s_mov_b64 s[12:13], s[8:9]
	s_mov_b32 m0, s29
	v_mov_b32_e32 v161, v9
	global_load_lds_dwordx4 v158, s[12:13]
	s_mov_b32 m0, s45
	s_nop 0
	global_load_lds_dwordx4 v160, s[12:13]
	s_add_u32 s12, s8, 0x40000
	s_addc_u32 s13, s9, 0
	s_add_i32 s46, s29, 0x4000
	s_mov_b32 m0, s46
	s_add_i32 s47, s29, 0x6000
	s_cmp_eq_u32 s6, 1
	global_load_lds_dwordx4 v158, s[12:13]
	s_mov_b32 m0, s47
	s_nop 0
	global_load_lds_dwordx4 v160, s[12:13]
	s_cselect_b64 s[12:13], -1, 0
	s_cmp_lg_u32 s6, 1
	s_cbranch_scc1 .LBB13_2042
	s_barrier
